# NA bias lookups batched in all four copies plus first grid sync switched from cg sync to the XCD barrier
# speedup vs baseline: 1.0096x; 1.0027x over previous
.LBB0_370:
	ds_read_b128 v[192:195], v171 offset:13312
	ds_read_b128 v[196:199], v171 offset:13344
	ds_read_b128 v[200:203], v171 offset:17920
	ds_read_b128 v[204:207], v171 offset:17952
	v_exp_f32_e32 v93, v48
	v_exp_f32_e32 v163, v32
	v_exp_f32_e32 v94, v49
	v_exp_f32_e32 v164, v33
	v_exp_f32_e32 v82, v52
	v_exp_f32_e32 v97, v36
	v_exp_f32_e32 v83, v53
	s_waitcnt vmcnt(3)
	v_exp_f32_e32 v140, v37
	v_exp_f32_e32 v88, v58
	v_exp_f32_e32 v89, v59
	v_exp_f32_e32 v80, v50
	v_exp_f32_e32 v95, v34
	v_exp_f32_e32 v81, v51
	v_exp_f32_e32 v96, v35
	v_exp_f32_e32 v84, v54
	v_exp_f32_e32 v141, v38
	v_exp_f32_e32 v85, v55
	v_exp_f32_e32 v142, v39
	v_exp_f32_e32 v86, v56
	v_exp_f32_e32 v143, v40
	v_exp_f32_e32 v87, v57
	s_waitcnt vmcnt(2)
	v_exp_f32_e32 v144, v41
	v_exp_f32_e32 v145, v42
	v_exp_f32_e32 v146, v43
	v_exp_f32_e32 v90, v60
	v_exp_f32_e32 v147, v44
	v_exp_f32_e32 v91, v61
	v_exp_f32_e32 v160, v45
	v_exp_f32_e32 v92, v62
	v_exp_f32_e32 v161, v46
	v_exp_f32_e32 v162, v63
	v_exp_f32_e32 v165, v47
	v_mov_b32_e32 v65, v64
	s_bitcmp1_b32 s1, 0
	v_mov_b32_e32 v66, v64
	v_mov_b32_e32 v67, v64
	v_mov_b32_e32 v68, v64
	v_mov_b32_e32 v69, v64
	v_mov_b32_e32 v70, v64
	v_mov_b32_e32 v71, v64
	v_mov_b32_e32 v72, v64
	v_mov_b32_e32 v73, v64
	v_mov_b32_e32 v74, v64
	v_mov_b32_e32 v75, v64
	v_mov_b32_e32 v76, v64
	v_mov_b32_e32 v77, v64
	v_mov_b32_e32 v78, v64
	v_mov_b32_e32 v79, v64
	v_cvt_pk_bf16_f32 v32, v93, v94
	v_cvt_pk_bf16_f32 v34, v82, v83
	v_cvt_pk_bf16_f32 v37, v88, v89
	v_cvt_pk_bf16_f32 v58, v163, v164
	v_cvt_pk_bf16_f32 v60, v97, v140
	s_cselect_b32 s1, 0x2400, 0
	v_cvt_pk_bf16_f32 v33, v80, v81
	v_cvt_pk_bf16_f32 v35, v84, v85
	v_cvt_pk_bf16_f32 v36, v86, v87
	v_cvt_pk_bf16_f32 v38, v90, v91
	v_cvt_pk_bf16_f32 v39, v92, v162
	v_cvt_pk_bf16_f32 v59, v95, v96
	v_cvt_pk_bf16_f32 v61, v141, v142
	v_cvt_pk_bf16_f32 v208, v143, v144
	v_cvt_pk_bf16_f32 v209, v145, v146
	v_cvt_pk_bf16_f32 v210, v147, v160
	v_cvt_pk_bf16_f32 v211, v161, v165
	s_waitcnt lgkmcnt(3)
	v_mfma_f32_32x32x16_bf16 v[42:57], v[192:195], v[100:103], v[64:79]
	s_waitcnt lgkmcnt(1)
	v_mfma_f32_32x32x16_bf16 v[64:79], v[200:203], v[100:103], v[64:79]
	ds_read_b128 v[192:195], v171 offset:13376
	ds_read_b128 v[200:203], v171 offset:17984
	v_mfma_f32_32x32x16_bf16 v[42:57], v[196:199], v[104:107], v[42:57]
	s_waitcnt lgkmcnt(2)
	v_mfma_f32_32x32x16_bf16 v[64:79], v[204:207], v[104:107], v[64:79]
	ds_read_b128 v[196:199], v171 offset:13408
	ds_read_b128 v[204:207], v171 offset:18016
	s_waitcnt lgkmcnt(3)
	v_mfma_f32_32x32x16_bf16 v[42:57], v[192:195], v[108:111], v[42:57]
	s_waitcnt lgkmcnt(2)
	v_mfma_f32_32x32x16_bf16 v[64:79], v[200:203], v[108:111], v[64:79]
	v_add_u32_e32 v40, s1, v153
	ds_read_b64_tr_b16 v[192:193], v40 offset:26624
	ds_read_b64_tr_b16 v[194:195], v40 offset:27776
	ds_read_b64_tr_b16 v[202:203], v40 offset:27840
	ds_read_b64_tr_b16 v[200:201], v40 offset:26688
	s_waitcnt lgkmcnt(5)
	v_mfma_f32_32x32x16_bf16 v[42:57], v[196:199], v[112:115], v[42:57]
	s_waitcnt lgkmcnt(4)
	v_mfma_f32_32x32x16_bf16 v[64:79], v[204:207], v[112:115], v[64:79]
	ds_read_b64_tr_b16 v[196:197], v40 offset:28928
	ds_read_b64_tr_b16 v[198:199], v40 offset:30080
	ds_read_b64_tr_b16 v[206:207], v40 offset:30144
	ds_read_b64_tr_b16 v[204:205], v40 offset:28992
	s_waitcnt lgkmcnt(6)
	v_mfma_f32_32x32x16_bf16 v[16:31], v[192:195], v[32:35], v[16:31]
	s_waitcnt lgkmcnt(4)
	v_mfma_f32_32x32x16_bf16 v[0:15], v[200:203], v[32:35], v[0:15]
	ds_read_b64_tr_b16 v[32:33], v40 offset:31232
	ds_read_b64_tr_b16 v[34:35], v40 offset:32384
	ds_read_b64_tr_b16 v[194:195], v40 offset:32448
	ds_read_b64_tr_b16 v[192:193], v40 offset:31296
	s_waitcnt lgkmcnt(6)
	v_mfma_f32_32x32x16_bf16 v[16:31], v[196:199], v[36:39], v[16:31]
	s_waitcnt lgkmcnt(4)
	v_mfma_f32_32x32x16_bf16 v[0:15], v[204:207], v[36:39], v[0:15]
	ds_read_b64_tr_b16 v[36:37], v40 offset:33536
	ds_read_b64_tr_b16 v[38:39], v40 offset:34688
	ds_read_b64_tr_b16 v[198:199], v40 offset:34752
	ds_read_b64_tr_b16 v[196:197], v40 offset:33600
	s_waitcnt lgkmcnt(6)
	v_mfma_f32_32x32x16_bf16 v[16:31], v[32:35], v[58:61], v[16:31]
	s_waitcnt lgkmcnt(4)
	v_mfma_f32_32x32x16_bf16 v[0:15], v[192:195], v[58:61], v[0:15]
	s_waitcnt lgkmcnt(2)
	v_mfma_f32_32x32x16_bf16 v[16:31], v[36:39], v[208:211], v[16:31]
	s_waitcnt lgkmcnt(0)
	v_mfma_f32_32x32x16_bf16 v[0:15], v[196:199], v[208:211], v[0:15]
	s_waitcnt vmcnt(1)
	ds_write_b128 v173, v[132:135] offset:35840
	s_waitcnt vmcnt(0)
	ds_write_b128 v174, v[136:139] offset:35840
	s_add_i32 s1, s15, 12
	v_add3_u32 v37, s8, v148, 16
	s_waitcnt lgkmcnt(0)
	s_barrier
	v_sub_u32_e32 v132, v37, v166
	v_sub_u32_e32 v63, v37, v170
	v_sub_u32_e32 v62, s1, v151
	v_lshlrev_b32_e32 v132, 2, v132
	v_mad_i32_i24 v132, v62, s5, v132
	v_add_u32_e32 v132, 0x163a0, v132
	ds_read2_b32 v[34:35], v132 offset0:0 offset1:1
	ds_read2_b32 v[38:39], v132 offset0:2 offset1:3
	ds_read2_b32 v[32:33], v132 offset0:8 offset1:9
	ds_read2_b32 v[40:41], v132 offset0:10 offset1:11
	v_sub_u32_e32 v62, s1, v169
	v_cmp_gt_u32_e64 s[38:39], 16, v63
	v_add_u32_e32 v63, 1, v63
	v_cmp_gt_u32_e64 s[40:41], 16, v63
	v_add_u32_e32 v63, 1, v63
	v_cmp_gt_u32_e64 s[42:43], 16, v63
	v_add_u32_e32 v63, 1, v63
	v_cmp_gt_u32_e64 s[44:45], 16, v63
	v_add_u32_e32 v63, 5, v63
	v_cmp_gt_u32_e64 s[46:47], 16, v63
	v_add_u32_e32 v63, 1, v63
	v_cmp_gt_u32_e64 s[48:49], 16, v63
	v_add_u32_e32 v63, 1, v63
	v_cmp_gt_u32_e64 s[50:51], 16, v63
	v_add_u32_e32 v63, 1, v63
	v_cmp_gt_u32_e64 s[52:53], 16, v63
	v_cmp_gt_u32_e64 s[54:55], 8, v62
	v_add_u32_e32 v62, 1, v62
	v_cmp_gt_u32_e64 s[6:7], 8, v62
	v_add_u32_e32 v62, 1, v62
	v_cmp_gt_u32_e64 s[10:11], 8, v62
	s_waitcnt lgkmcnt(0)
	v_add_f32_e32 v34, v42, v34
	v_add_f32_e32 v35, v43, v35
	v_add_f32_e32 v38, v44, v38
	v_add_f32_e32 v39, v45, v39
	v_add_f32_e32 v32, v46, v32
	v_add_f32_e32 v33, v47, v33
	v_add_f32_e32 v40, v48, v40
	v_add_f32_e32 v41, v49, v41
	s_and_b64 vcc, s[38:39], s[54:55]
	v_cndmask_b32_e32 v34, v233, v34, vcc
	s_and_b64 vcc, s[40:41], s[54:55]
	v_cndmask_b32_e32 v35, v233, v35, vcc
	s_and_b64 vcc, s[42:43], s[54:55]
	v_cndmask_b32_e32 v38, v233, v38, vcc
	s_and_b64 vcc, s[44:45], s[54:55]
	v_cndmask_b32_e32 v39, v233, v39, vcc
	s_and_b64 vcc, s[46:47], s[54:55]
	v_cndmask_b32_e32 v42, v233, v32, vcc
	s_and_b64 vcc, s[48:49], s[54:55]
	v_cndmask_b32_e32 v43, v233, v33, vcc
	s_and_b64 vcc, s[50:51], s[54:55]
	v_cndmask_b32_e32 v46, v233, v40, vcc
	s_and_b64 vcc, s[52:53], s[54:55]
	v_cndmask_b32_e32 v47, v233, v41, vcc
	v_add_u32_e32 v62, 1, v62
	v_cmp_gt_u32_e64 s[54:55], 8, v62
	ds_read2_b32 v[32:33], v132 offset0:62 offset1:63
	ds_read2_b32 v[36:37], v132 offset0:64 offset1:65
	ds_read2_b32 v[40:41], v132 offset0:70 offset1:71
	ds_read2_b32 v[44:45], v132 offset0:72 offset1:73
	s_waitcnt lgkmcnt(0)
	v_add_f32_e32 v32, v64, v32
	v_add_f32_e32 v33, v65, v33
	v_add_f32_e32 v36, v66, v36
	v_add_f32_e32 v37, v67, v37
	v_add_f32_e32 v40, v68, v40
	v_add_f32_e32 v41, v69, v41
	v_add_f32_e32 v44, v70, v44
	v_add_f32_e32 v45, v71, v45
	s_and_b64 vcc, s[38:39], s[10:11]
	v_cndmask_b32_e32 v32, v233, v32, vcc
	s_and_b64 vcc, s[40:41], s[10:11]
	v_cndmask_b32_e32 v33, v233, v33, vcc
	s_and_b64 vcc, s[42:43], s[10:11]
	v_cndmask_b32_e32 v36, v233, v36, vcc
	s_and_b64 vcc, s[44:45], s[10:11]
	v_cndmask_b32_e32 v37, v233, v37, vcc
	s_and_b64 vcc, s[46:47], s[10:11]
	v_cndmask_b32_e32 v40, v233, v40, vcc
	s_and_b64 vcc, s[48:49], s[10:11]
	v_cndmask_b32_e32 v41, v233, v41, vcc
	s_and_b64 vcc, s[50:51], s[10:11]
	v_cndmask_b32_e32 v44, v233, v44, vcc
	s_and_b64 vcc, s[52:53], s[10:11]
	v_cndmask_b32_e32 v45, v233, v45, vcc
	ds_read2_b32 v[58:59], v132 offset0:31 offset1:32
	ds_read2_b32 v[60:61], v132 offset0:33 offset1:34
	ds_read2_b32 v[62:63], v132 offset0:39 offset1:40
	ds_read2_b32 v[64:65], v132 offset0:41 offset1:42
	s_waitcnt lgkmcnt(0)
	v_add_f32_e32 v58, v50, v58
	v_add_f32_e32 v59, v51, v59
	v_add_f32_e32 v60, v52, v60
	v_add_f32_e32 v61, v53, v61
	v_add_f32_e32 v62, v54, v62
	v_add_f32_e32 v63, v55, v63
	v_add_f32_e32 v64, v56, v64
	v_add_f32_e32 v65, v57, v65
	s_and_b64 vcc, s[38:39], s[6:7]
	v_cndmask_b32_e32 v58, v233, v58, vcc
	s_and_b64 vcc, s[40:41], s[6:7]
	v_cndmask_b32_e32 v59, v233, v59, vcc
	s_and_b64 vcc, s[42:43], s[6:7]
	v_cndmask_b32_e32 v60, v233, v60, vcc
	s_and_b64 vcc, s[44:45], s[6:7]
	v_cndmask_b32_e32 v61, v233, v61, vcc
	s_and_b64 vcc, s[46:47], s[6:7]
	v_cndmask_b32_e32 v62, v233, v62, vcc
	s_and_b64 vcc, s[48:49], s[6:7]
	v_cndmask_b32_e32 v63, v233, v63, vcc
	s_and_b64 vcc, s[50:51], s[6:7]
	v_cndmask_b32_e32 v64, v233, v64, vcc
	s_and_b64 vcc, s[52:53], s[6:7]
	v_cndmask_b32_e32 v65, v233, v65, vcc
	ds_read2_b32 v[48:49], v132 offset0:93 offset1:94
	ds_read2_b32 v[50:51], v132 offset0:95 offset1:96
	ds_read2_b32 v[52:53], v132 offset0:101 offset1:102
	ds_read2_b32 v[54:55], v132 offset0:103 offset1:104
	s_waitcnt lgkmcnt(0)
	v_add_f32_e32 v48, v72, v48
	v_add_f32_e32 v49, v73, v49
	v_add_f32_e32 v50, v74, v50
	v_add_f32_e32 v51, v75, v51
	v_add_f32_e32 v52, v76, v52
	v_add_f32_e32 v53, v77, v53
	v_add_f32_e32 v54, v78, v54
	v_add_f32_e32 v55, v79, v55
	s_and_b64 vcc, s[38:39], s[54:55]
	v_cndmask_b32_e32 v48, v233, v48, vcc
	s_and_b64 vcc, s[40:41], s[54:55]
	v_cndmask_b32_e32 v49, v233, v49, vcc
	s_and_b64 vcc, s[42:43], s[54:55]
	v_cndmask_b32_e32 v50, v233, v50, vcc
	s_and_b64 vcc, s[44:45], s[54:55]
	v_cndmask_b32_e32 v51, v233, v51, vcc
	s_and_b64 vcc, s[46:47], s[54:55]
	v_cndmask_b32_e32 v52, v233, v52, vcc
	s_and_b64 vcc, s[48:49], s[54:55]
	v_cndmask_b32_e32 v53, v233, v53, vcc
	s_and_b64 vcc, s[50:51], s[54:55]
	v_cndmask_b32_e32 v54, v233, v54, vcc
	s_and_b64 vcc, s[52:53], s[54:55]
	v_cndmask_b32_e32 v55, v233, v55, vcc
	v_add_f32_e32 v56, v163, v93
	v_add_f32_e32 v57, v164, v94
	v_add_f32_e32 v56, 0, v56
	v_add_f32_e32 v56, v57, v56
	v_add_f32_e32 v57, v95, v80
	v_add_f32_e32 v56, v57, v56
	v_add_f32_e32 v57, v96, v81
	v_add_f32_e32 v56, v57, v56
	v_add_f32_e32 v57, v97, v82
	v_add_f32_e32 v56, v57, v56
	v_add_f32_e32 v57, v140, v83
	v_add_f32_e32 v56, v57, v56
	v_add_f32_e32 v57, v141, v84
	v_add_f32_e32 v56, v57, v56
	v_add_f32_e32 v57, v142, v85
	v_add_f32_e32 v56, v57, v56
	v_add_f32_e32 v57, v143, v86
	v_add_f32_e32 v56, v57, v56
	v_add_f32_e32 v57, v144, v87
	v_add_f32_e32 v56, v57, v56
	v_add_f32_e32 v57, v145, v88
	v_add_f32_e32 v56, v57, v56
	v_add_f32_e32 v57, v146, v89
	v_add_f32_e32 v56, v57, v56
	v_add_f32_e32 v57, v147, v90
	v_add_f32_e32 v56, v57, v56
	v_add_f32_e32 v57, v160, v91
	v_add_f32_e32 v56, v57, v56
	v_add_f32_e32 v57, v161, v92
	v_add_f32_e32 v56, v57, v56
	v_add_f32_e32 v57, v165, v162
	v_add_f32_e32 v56, v57, v56
	v_max3_f32 v57, v34, v35, v32
	v_max3_f32 v66, v38, v39, v33
	v_add_f32_e32 v56, v159, v56
	v_max3_f32 v57, v57, v36, v37
	v_max3_f32 v66, v66, v46, v47
	s_nop 0
	v_max3_f32 v57, v57, v42, v43
	v_max3_f32 v66, v66, v44, v45
	s_nop 0
	v_max3_f32 v57, v57, v40, v41
	v_max3_f32 v66, v66, v60, v61
	s_nop 0
	v_max3_f32 v57, v57, v58, v59
	v_max3_f32 v66, v66, v50, v51
	s_nop 0
	v_max3_f32 v57, v57, v48, v49
	v_max3_f32 v66, v66, v64, v65
	s_nop 0
	v_max3_f32 v57, v57, v62, v63
	v_max3_f32 v66, v66, v54, v55
	s_nop 0
	v_max3_f32 v57, v57, v52, v53
	s_nop 0
	v_max3_f32 v57, v57, v66, v66
	ds_bpermute_b32 v66, v172, v57
	s_waitcnt lgkmcnt(0)
	v_max3_f32 v57, v57, v66, v57
	s_nop 0
	v_cmp_lt_f32_e32 vcc, s78, v57
	s_cbranch_vccz .LBB0_436
	v_max_f32_e32 v57, v57, v57
	v_max_f32_e32 v57, 0, v57
	v_exp_f32_e64 v66, -v57
	v_sub_f32_e32 v65, v65, v57
	v_sub_f32_e32 v64, v64, v57
	v_sub_f32_e32 v63, v63, v57
	v_mul_f32_e32 v56, v56, v66
	v_pk_mul_f32 v[30:31], v[30:31], v[66:67] op_sel_hi:[1,0]
	v_pk_mul_f32 v[28:29], v[28:29], v[66:67] op_sel_hi:[1,0]
	v_pk_mul_f32 v[26:27], v[26:27], v[66:67] op_sel_hi:[1,0]
	v_pk_mul_f32 v[24:25], v[24:25], v[66:67] op_sel_hi:[1,0]
	v_pk_mul_f32 v[22:23], v[22:23], v[66:67] op_sel_hi:[1,0]
	v_pk_mul_f32 v[20:21], v[20:21], v[66:67] op_sel_hi:[1,0]
	v_pk_mul_f32 v[18:19], v[18:19], v[66:67] op_sel_hi:[1,0]
	v_pk_mul_f32 v[16:17], v[16:17], v[66:67] op_sel_hi:[1,0]
	v_pk_mul_f32 v[14:15], v[14:15], v[66:67] op_sel_hi:[1,0]
	v_pk_mul_f32 v[12:13], v[12:13], v[66:67] op_sel_hi:[1,0]
	v_pk_mul_f32 v[10:11], v[10:11], v[66:67] op_sel_hi:[1,0]
	v_pk_mul_f32 v[8:9], v[8:9], v[66:67] op_sel_hi:[1,0]
	v_pk_mul_f32 v[6:7], v[6:7], v[66:67] op_sel_hi:[1,0]
	v_pk_mul_f32 v[4:5], v[4:5], v[66:67] op_sel_hi:[1,0]
	v_pk_mul_f32 v[2:3], v[2:3], v[66:67] op_sel_hi:[1,0]
	v_pk_mul_f32 v[0:1], v[0:1], v[66:67] op_sel_hi:[1,0]
	v_sub_f32_e32 v62, v62, v57
	v_sub_f32_e32 v61, v61, v57
	v_sub_f32_e32 v60, v60, v57
	v_sub_f32_e32 v59, v59, v57
	v_sub_f32_e32 v58, v58, v57
	v_sub_f32_e32 v47, v47, v57
	v_sub_f32_e32 v46, v46, v57
	v_sub_f32_e32 v43, v43, v57
	v_sub_f32_e32 v42, v42, v57
	v_sub_f32_e32 v39, v39, v57
	v_sub_f32_e32 v38, v38, v57
	v_sub_f32_e32 v35, v35, v57
	v_sub_f32_e32 v34, v34, v57
	v_sub_f32_e32 v55, v55, v57
	v_sub_f32_e32 v54, v54, v57
	v_sub_f32_e32 v53, v53, v57
	v_sub_f32_e32 v52, v52, v57
	v_sub_f32_e32 v51, v51, v57
	v_sub_f32_e32 v50, v50, v57
	v_sub_f32_e32 v49, v49, v57
	v_sub_f32_e32 v48, v48, v57
	v_sub_f32_e32 v45, v45, v57
	v_sub_f32_e32 v44, v44, v57
	v_sub_f32_e32 v41, v41, v57
	v_sub_f32_e32 v40, v40, v57
	v_sub_f32_e32 v37, v37, v57
	v_sub_f32_e32 v36, v36, v57
	v_sub_f32_e32 v33, v33, v57
	v_sub_f32_e32 v32, v32, v57

.LBB0_1351:
	s_cmp_lg_u32 s61, 0
	s_nop 0
	s_waitcnt vmcnt(0)
	s_waitcnt vmcnt(0) lgkmcnt(0)
	s_barrier
	s_mov_b64 s[0:1], exec
	v_readlane_b32 s6, v252, 11
	v_readlane_b32 s7, v252, 12
	s_and_b64 s[6:7], s[0:1], s[6:7]
	s_mov_b64 exec, s[6:7]
	s_cbranch_execz .LBB0_1404
	s_add_i32 s12, 0, 0x20000
	v_mov_b32_e32 v0, s12
	s_waitcnt vmcnt(0) expcnt(0) lgkmcnt(0)
	ds_read_b32 v2, v0
	v_readlane_b32 s6, v254, 40
	s_waitcnt lgkmcnt(0)
	v_cmp_ne_u32_e32 vcc, 0, v2
	v_mov_b32_e32 v0, s6
	ds_read_b32 v0, v0
	s_cbranch_vccnz .LBB0_1368
	v_readlane_b32 s8, v252, 9
	v_readlane_b32 s9, v252, 10
	s_load_dwordx2 s[6:7], s[8:9], 0x4
	s_mov_b32 s14, 1
	s_waitcnt lgkmcnt(0)
	s_mul_i32 s13, s6, s3
	s_mul_i32 s13, s13, s7
	s_branch .LBB0_1356
